# compress MLP first-layer K loop rewritten straight-line: 8 half-trips of two k-steps, each half's 14 loads issued together into one of two register sets and prefetched two halves ahead (was 80 seriali
# speedup vs baseline: 1.0092x; 1.0024x over previous
; DEV float lo_f(unsigned w) { return __uint_as_float(w << 16); }
; DEV float hi_f(unsigned w) { return __uint_as_float(w & 0xFFFF0000u); }
; DEV f32x4 mfma16(bf16x8 a, bf16x8 b, f32x4 c) { return __builtin_amdgcn_mfma_f32_16x16x32_bf16(a, b, c, 0, 0, 0); }
; __device__ void compress_block_item(const Params& P, int l, int bitem, char* smem) {
;     ...
; #pragma unroll 4
;   for (int k2 = 0; k2 < 16; ++k2) {
;     const int ks = w * 16 + k2;
;     const int tl = ks >> 1, d0 = (ks & 1) * 32 + kq * 8;
;     const uint4 raw = *(const uint4*)(src + (size_t)tl * HS + d0);
;     const float4 p0 = *(const float4*)(pos + tl * 64 + d0), p1 = *(const float4*)(pos + tl * 64 + d0 + 4);
;     float v[8];
;     v[0] = lo_f(raw.x) + p0.x; v[1] = hi_f(raw.x) + p0.y; v[2] = lo_f(raw.y) + p0.z; v[3] = hi_f(raw.y) + p0.w;
;     v[4] = lo_f(raw.z) + p1.x; v[5] = hi_f(raw.z) + p1.y; v[6] = lo_f(raw.w) + p1.z; v[7] = hi_f(raw.w) + p1.w;
;     const bf16x8 af = pack8(v);
; #pragma unroll
;     for (int nt = 0; nt < 4; ++nt) {
;       const bf16x8 bfr = *(const bf16x8*)(W1T + (size_t)(nt * 16 + r16) * 2048 + ks * 32 + kq * 8);
;       acc[nt] = mfma16(af, bfr, acc[nt]);
;     }
;   }
.LBB0_301:
	v_ashrrev_i32_e32 v240, 1, v37
	v_mov_b32_e32 v241, v177
	v_mad_i64_i32 v[236:237], s[44:45], v240, s46, v[16:17]
	v_lshlrev_b32_e32 v242, 8, v240
	v_mov_b32_e32 v243, v177
	v_lshl_add_u64 v[238:239], v[242:243], 0, v[18:19]
	v_add_co_u32_e32 v28, vcc, s2, v20
	s_nop 1
	v_addc_co_u32_e32 v29, vcc, 0, v21, vcc
	v_add_co_u32_e32 v26, vcc, s42, v20
	s_nop 1
	v_addc_co_u32_e32 v27, vcc, 0, v21, vcc
	v_add_co_u32_e32 v24, vcc, s43, v20
	s_nop 1
	v_addc_co_u32_e32 v25, vcc, 0, v21, vcc
	s_mov_b64 s[40:41], 0x1030
	global_load_dwordx4 v[88:91], v[236:237], off
	global_load_dwordx4 v[92:95], v[238:239], off
	global_load_dwordx4 v[96:99], v[238:239], off offset:16
	global_load_dwordx4 v[100:103], v[236:237], off offset:64
	global_load_dwordx4 v[104:107], v[238:239], off offset:128
	global_load_dwordx4 v[108:111], v[238:239], off offset:144
	global_load_dwordx4 v[112:115], v[20:21], off
	global_load_dwordx4 v[116:119], v[28:29], off
	global_load_dwordx4 v[120:123], v[26:27], off
	global_load_dwordx4 v[124:127], v[24:25], off
	global_load_dwordx4 v[128:131], v[20:21], off offset:64
	global_load_dwordx4 v[132:135], v[28:29], off offset:64
	global_load_dwordx4 v[136:139], v[26:27], off offset:64
	global_load_dwordx4 v[140:143], v[24:25], off offset:64
	v_lshl_add_u64 v[236:237], v[236:237], 0, s[40:41]
	global_load_dwordx4 v[144:147], v[236:237], off
	global_load_dwordx4 v[148:151], v[238:239], off offset:256
	global_load_dwordx4 v[152:155], v[238:239], off offset:272
	global_load_dwordx4 v[156:159], v[236:237], off offset:64
	global_load_dwordx4 v[160:163], v[238:239], off offset:384
	global_load_dwordx4 v[164:167], v[238:239], off offset:400
	global_load_dwordx4 v[168:171], v[20:21], off offset:128
	global_load_dwordx4 v[172:175], v[28:29], off offset:128
	global_load_dwordx4 v[180:183], v[26:27], off offset:128
	global_load_dwordx4 v[184:187], v[24:25], off offset:128
	global_load_dwordx4 v[188:191], v[20:21], off offset:192
	global_load_dwordx4 v[192:195], v[28:29], off offset:192
	global_load_dwordx4 v[196:199], v[26:27], off offset:192
	global_load_dwordx4 v[228:231], v[24:25], off offset:192
	v_lshl_add_u64 v[236:237], v[236:237], 0, s[40:41]
	s_waitcnt vmcnt(14)
	v_lshlrev_b32_e32 v42, 16, v88
	v_and_b32_e32 v43, 0xffff0000, v88
	v_lshlrev_b32_e32 v44, 16, v89
	v_and_b32_e32 v45, 0xffff0000, v89
	v_lshlrev_b32_e32 v46, 16, v90
	v_and_b32_e32 v47, 0xffff0000, v90
	v_lshlrev_b32_e32 v48, 16, v91
	v_and_b32_e32 v49, 0xffff0000, v91
	v_pk_add_f32 v[42:43], v[92:93], v[42:43]
	v_pk_add_f32 v[44:45], v[94:95], v[44:45]
	v_pk_add_f32 v[46:47], v[96:97], v[46:47]
	v_pk_add_f32 v[48:49], v[98:99], v[48:49]
	v_cvt_pk_bf16_f32 v38, v42, v43
	v_cvt_pk_bf16_f32 v39, v44, v45
	v_cvt_pk_bf16_f32 v40, v46, v47
	v_cvt_pk_bf16_f32 v41, v48, v49
	s_nop 1
	v_mfma_f32_16x16x32_bf16 v[0:3], v[38:41], v[112:115], v[0:3]
	v_mfma_f32_16x16x32_bf16 v[4:7], v[38:41], v[116:119], v[4:7]
	v_mfma_f32_16x16x32_bf16 v[8:11], v[38:41], v[120:123], v[8:11]
	v_mfma_f32_16x16x32_bf16 v[12:15], v[38:41], v[124:127], v[12:15]
	v_lshlrev_b32_e32 v42, 16, v100
	v_and_b32_e32 v43, 0xffff0000, v100
	v_lshlrev_b32_e32 v44, 16, v101
	v_and_b32_e32 v45, 0xffff0000, v101
	v_lshlrev_b32_e32 v46, 16, v102
	v_and_b32_e32 v47, 0xffff0000, v102
	v_lshlrev_b32_e32 v48, 16, v103
	v_and_b32_e32 v49, 0xffff0000, v103
	v_pk_add_f32 v[42:43], v[104:105], v[42:43]
	v_pk_add_f32 v[44:45], v[106:107], v[44:45]
	v_pk_add_f32 v[46:47], v[108:109], v[46:47]
	v_pk_add_f32 v[48:49], v[110:111], v[48:49]
	v_cvt_pk_bf16_f32 v232, v42, v43
	v_cvt_pk_bf16_f32 v233, v44, v45
	v_cvt_pk_bf16_f32 v234, v46, v47
	v_cvt_pk_bf16_f32 v235, v48, v49
	s_nop 1
	v_mfma_f32_16x16x32_bf16 v[0:3], v[232:235], v[128:131], v[0:3]
	v_mfma_f32_16x16x32_bf16 v[4:7], v[232:235], v[132:135], v[4:7]
	v_mfma_f32_16x16x32_bf16 v[8:11], v[232:235], v[136:139], v[8:11]
	v_mfma_f32_16x16x32_bf16 v[12:15], v[232:235], v[140:143], v[12:15]
	global_load_dwordx4 v[88:91], v[236:237], off
	global_load_dwordx4 v[92:95], v[238:239], off offset:512
	global_load_dwordx4 v[96:99], v[238:239], off offset:528
	global_load_dwordx4 v[100:103], v[236:237], off offset:64
	global_load_dwordx4 v[104:107], v[238:239], off offset:640
	global_load_dwordx4 v[108:111], v[238:239], off offset:656
	global_load_dwordx4 v[112:115], v[20:21], off offset:256
	global_load_dwordx4 v[116:119], v[28:29], off offset:256
	global_load_dwordx4 v[120:123], v[26:27], off offset:256
	global_load_dwordx4 v[124:127], v[24:25], off offset:256
	global_load_dwordx4 v[128:131], v[20:21], off offset:320
	global_load_dwordx4 v[132:135], v[28:29], off offset:320
	global_load_dwordx4 v[136:139], v[26:27], off offset:320
	global_load_dwordx4 v[140:143], v[24:25], off offset:320
	v_lshl_add_u64 v[236:237], v[236:237], 0, s[40:41]
	s_waitcnt vmcnt(14)
; DEV float lo_f(unsigned w) { return __uint_as_float(w << 16); }
; DEV float hi_f(unsigned w) { return __uint_as_float(w & 0xFFFF0000u); }
; DEV f32x4 mfma16(bf16x8 a, bf16x8 b, f32x4 c) { return __builtin_amdgcn_mfma_f32_16x16x32_bf16(a, b, c, 0, 0, 0); }
; __device__ void compress_block_item(const Params& P, int l, int bitem, char* smem) {
;     ...
; #pragma unroll 4
;   for (int k2 = 0; k2 < 16; ++k2) {
;     const int ks = w * 16 + k2;
;     const int tl = ks >> 1, d0 = (ks & 1) * 32 + kq * 8;
;     const uint4 raw = *(const uint4*)(src + (size_t)tl * HS + d0);
;     const float4 p0 = *(const float4*)(pos + tl * 64 + d0), p1 = *(const float4*)(pos + tl * 64 + d0 + 4);
;     float v[8];
;     v[0] = lo_f(raw.x) + p0.x; v[1] = hi_f(raw.x) + p0.y; v[2] = lo_f(raw.y) + p0.z; v[3] = hi_f(raw.y) + p0.w;
;     v[4] = lo_f(raw.z) + p1.x; v[5] = hi_f(raw.z) + p1.y; v[6] = lo_f(raw.w) + p1.z; v[7] = hi_f(raw.w) + p1.w;
;     const bf16x8 af = pack8(v);
; #pragma unroll
;     for (int nt = 0; nt < 4; ++nt) {
;       const bf16x8 bfr = *(const bf16x8*)(W1T + (size_t)(nt * 16 + r16) * 2048 + ks * 32 + kq * 8);
;       acc[nt] = mfma16(af, bfr, acc[nt]);
;     }
;   }
	v_lshlrev_b32_e32 v42, 16, v144
	v_and_b32_e32 v43, 0xffff0000, v144
	v_lshlrev_b32_e32 v44, 16, v145
	v_and_b32_e32 v45, 0xffff0000, v145
	v_lshlrev_b32_e32 v46, 16, v146
	v_and_b32_e32 v47, 0xffff0000, v146
	v_lshlrev_b32_e32 v48, 16, v147
	v_and_b32_e32 v49, 0xffff0000, v147
	v_pk_add_f32 v[42:43], v[148:149], v[42:43]
	v_pk_add_f32 v[44:45], v[150:151], v[44:45]
	v_pk_add_f32 v[46:47], v[152:153], v[46:47]
	v_pk_add_f32 v[48:49], v[154:155], v[48:49]
	v_cvt_pk_bf16_f32 v38, v42, v43
	v_cvt_pk_bf16_f32 v39, v44, v45
	v_cvt_pk_bf16_f32 v40, v46, v47
	v_cvt_pk_bf16_f32 v41, v48, v49
	s_nop 1
	v_mfma_f32_16x16x32_bf16 v[0:3], v[38:41], v[168:171], v[0:3]
	v_mfma_f32_16x16x32_bf16 v[4:7], v[38:41], v[172:175], v[4:7]
	v_mfma_f32_16x16x32_bf16 v[8:11], v[38:41], v[180:183], v[8:11]
	v_mfma_f32_16x16x32_bf16 v[12:15], v[38:41], v[184:187], v[12:15]
	v_lshlrev_b32_e32 v42, 16, v156
	v_and_b32_e32 v43, 0xffff0000, v156
	v_lshlrev_b32_e32 v44, 16, v157
	v_and_b32_e32 v45, 0xffff0000, v157
	v_lshlrev_b32_e32 v46, 16, v158
	v_and_b32_e32 v47, 0xffff0000, v158
	v_lshlrev_b32_e32 v48, 16, v159
	v_and_b32_e32 v49, 0xffff0000, v159
	v_pk_add_f32 v[42:43], v[160:161], v[42:43]
	v_pk_add_f32 v[44:45], v[162:163], v[44:45]
	v_pk_add_f32 v[46:47], v[164:165], v[46:47]
	v_pk_add_f32 v[48:49], v[166:167], v[48:49]
	v_cvt_pk_bf16_f32 v232, v42, v43
	v_cvt_pk_bf16_f32 v233, v44, v45
	v_cvt_pk_bf16_f32 v234, v46, v47
	v_cvt_pk_bf16_f32 v235, v48, v49
	s_nop 1
	v_mfma_f32_16x16x32_bf16 v[0:3], v[232:235], v[188:191], v[0:3]
	v_mfma_f32_16x16x32_bf16 v[4:7], v[232:235], v[192:195], v[4:7]
	v_mfma_f32_16x16x32_bf16 v[8:11], v[232:235], v[196:199], v[8:11]
	v_mfma_f32_16x16x32_bf16 v[12:15], v[232:235], v[228:231], v[12:15]
	global_load_dwordx4 v[144:147], v[236:237], off
	global_load_dwordx4 v[148:151], v[238:239], off offset:768
	global_load_dwordx4 v[152:155], v[238:239], off offset:784
	global_load_dwordx4 v[156:159], v[236:237], off offset:64
	global_load_dwordx4 v[160:163], v[238:239], off offset:896
	global_load_dwordx4 v[164:167], v[238:239], off offset:912
	global_load_dwordx4 v[168:171], v[20:21], off offset:384
	global_load_dwordx4 v[172:175], v[28:29], off offset:384
	global_load_dwordx4 v[180:183], v[26:27], off offset:384
	global_load_dwordx4 v[184:187], v[24:25], off offset:384
	global_load_dwordx4 v[188:191], v[20:21], off offset:448
	global_load_dwordx4 v[192:195], v[28:29], off offset:448
	global_load_dwordx4 v[196:199], v[26:27], off offset:448
	global_load_dwordx4 v[228:231], v[24:25], off offset:448
	v_lshl_add_u64 v[236:237], v[236:237], 0, s[40:41]
	s_waitcnt vmcnt(14)
	v_lshlrev_b32_e32 v42, 16, v88
	v_and_b32_e32 v43, 0xffff0000, v88
	v_lshlrev_b32_e32 v44, 16, v89
	v_and_b32_e32 v45, 0xffff0000, v89
	v_lshlrev_b32_e32 v46, 16, v90
	v_and_b32_e32 v47, 0xffff0000, v90
	v_lshlrev_b32_e32 v48, 16, v91
	v_and_b32_e32 v49, 0xffff0000, v91
	v_pk_add_f32 v[42:43], v[92:93], v[42:43]
	v_pk_add_f32 v[44:45], v[94:95], v[44:45]
	v_pk_add_f32 v[46:47], v[96:97], v[46:47]
	v_pk_add_f32 v[48:49], v[98:99], v[48:49]
	v_cvt_pk_bf16_f32 v38, v42, v43
	v_cvt_pk_bf16_f32 v39, v44, v45
	v_cvt_pk_bf16_f32 v40, v46, v47
	v_cvt_pk_bf16_f32 v41, v48, v49
	s_nop 1
	v_mfma_f32_16x16x32_bf16 v[0:3], v[38:41], v[112:115], v[0:3]
	v_mfma_f32_16x16x32_bf16 v[4:7], v[38:41], v[116:119], v[4:7]
	v_mfma_f32_16x16x32_bf16 v[8:11], v[38:41], v[120:123], v[8:11]
	v_mfma_f32_16x16x32_bf16 v[12:15], v[38:41], v[124:127], v[12:15]
	v_lshlrev_b32_e32 v42, 16, v100
	v_and_b32_e32 v43, 0xffff0000, v100
	v_lshlrev_b32_e32 v44, 16, v101
	v_and_b32_e32 v45, 0xffff0000, v101
	v_lshlrev_b32_e32 v46, 16, v102
	v_and_b32_e32 v47, 0xffff0000, v102
	v_lshlrev_b32_e32 v48, 16, v103
	v_and_b32_e32 v49, 0xffff0000, v103
	v_pk_add_f32 v[42:43], v[104:105], v[42:43]
	v_pk_add_f32 v[44:45], v[106:107], v[44:45]
	v_pk_add_f32 v[46:47], v[108:109], v[46:47]
	v_pk_add_f32 v[48:49], v[110:111], v[48:49]
	v_cvt_pk_bf16_f32 v232, v42, v43
	v_cvt_pk_bf16_f32 v233, v44, v45
	v_cvt_pk_bf16_f32 v234, v46, v47
	v_cvt_pk_bf16_f32 v235, v48, v49
	s_nop 1
	v_mfma_f32_16x16x32_bf16 v[0:3], v[232:235], v[128:131], v[0:3]
	v_mfma_f32_16x16x32_bf16 v[4:7], v[232:235], v[132:135], v[4:7]
	v_mfma_f32_16x16x32_bf16 v[8:11], v[232:235], v[136:139], v[8:11]
	v_mfma_f32_16x16x32_bf16 v[12:15], v[232:235], v[140:143], v[12:15]
	global_load_dwordx4 v[88:91], v[236:237], off
	global_load_dwordx4 v[92:95], v[238:239], off offset:1024
	global_load_dwordx4 v[96:99], v[238:239], off offset:1040
	global_load_dwordx4 v[100:103], v[236:237], off offset:64
	global_load_dwordx4 v[104:107], v[238:239], off offset:1152
	global_load_dwordx4 v[108:111], v[238:239], off offset:1168
	global_load_dwordx4 v[112:115], v[20:21], off offset:512
	global_load_dwordx4 v[116:119], v[28:29], off offset:512
	global_load_dwordx4 v[120:123], v[26:27], off offset:512
	global_load_dwordx4 v[124:127], v[24:25], off offset:512
	global_load_dwordx4 v[128:131], v[20:21], off offset:576
	global_load_dwordx4 v[132:135], v[28:29], off offset:576
	global_load_dwordx4 v[136:139], v[26:27], off offset:576
	global_load_dwordx4 v[140:143], v[24:25], off offset:576
	v_lshl_add_u64 v[236:237], v[236:237], 0, s[40:41]
	s_waitcnt vmcnt(14)
; DEV float lo_f(unsigned w) { return __uint_as_float(w << 16); }
; DEV float hi_f(unsigned w) { return __uint_as_float(w & 0xFFFF0000u); }
; DEV f32x4 mfma16(bf16x8 a, bf16x8 b, f32x4 c) { return __builtin_amdgcn_mfma_f32_16x16x32_bf16(a, b, c, 0, 0, 0); }
; __device__ void compress_block_item(const Params& P, int l, int bitem, char* smem) {
;     ...
; #pragma unroll 4
;   for (int k2 = 0; k2 < 16; ++k2) {
;     const int ks = w * 16 + k2;
;     const int tl = ks >> 1, d0 = (ks & 1) * 32 + kq * 8;
;     const uint4 raw = *(const uint4*)(src + (size_t)tl * HS + d0);
;     const float4 p0 = *(const float4*)(pos + tl * 64 + d0), p1 = *(const float4*)(pos + tl * 64 + d0 + 4);
;     float v[8];
;     v[0] = lo_f(raw.x) + p0.x; v[1] = hi_f(raw.x) + p0.y; v[2] = lo_f(raw.y) + p0.z; v[3] = hi_f(raw.y) + p0.w;
;     v[4] = lo_f(raw.z) + p1.x; v[5] = hi_f(raw.z) + p1.y; v[6] = lo_f(raw.w) + p1.z; v[7] = hi_f(raw.w) + p1.w;
;     const bf16x8 af = pack8(v);
; #pragma unroll
;     for (int nt = 0; nt < 4; ++nt) {
;       const bf16x8 bfr = *(const bf16x8*)(W1T + (size_t)(nt * 16 + r16) * 2048 + ks * 32 + kq * 8);
;       acc[nt] = mfma16(af, bfr, acc[nt]);
;     }
;   }
	v_lshlrev_b32_e32 v42, 16, v144
	v_and_b32_e32 v43, 0xffff0000, v144
	v_lshlrev_b32_e32 v44, 16, v145
	v_and_b32_e32 v45, 0xffff0000, v145
	v_lshlrev_b32_e32 v46, 16, v146
	v_and_b32_e32 v47, 0xffff0000, v146
	v_lshlrev_b32_e32 v48, 16, v147
	v_and_b32_e32 v49, 0xffff0000, v147
	v_pk_add_f32 v[42:43], v[148:149], v[42:43]
	v_pk_add_f32 v[44:45], v[150:151], v[44:45]
	v_pk_add_f32 v[46:47], v[152:153], v[46:47]
	v_pk_add_f32 v[48:49], v[154:155], v[48:49]
	v_cvt_pk_bf16_f32 v38, v42, v43
	v_cvt_pk_bf16_f32 v39, v44, v45
	v_cvt_pk_bf16_f32 v40, v46, v47
	v_cvt_pk_bf16_f32 v41, v48, v49
	s_nop 1
	v_mfma_f32_16x16x32_bf16 v[0:3], v[38:41], v[168:171], v[0:3]
	v_mfma_f32_16x16x32_bf16 v[4:7], v[38:41], v[172:175], v[4:7]
	v_mfma_f32_16x16x32_bf16 v[8:11], v[38:41], v[180:183], v[8:11]
	v_mfma_f32_16x16x32_bf16 v[12:15], v[38:41], v[184:187], v[12:15]
	v_lshlrev_b32_e32 v42, 16, v156
	v_and_b32_e32 v43, 0xffff0000, v156
	v_lshlrev_b32_e32 v44, 16, v157
	v_and_b32_e32 v45, 0xffff0000, v157
	v_lshlrev_b32_e32 v46, 16, v158
	v_and_b32_e32 v47, 0xffff0000, v158
	v_lshlrev_b32_e32 v48, 16, v159
	v_and_b32_e32 v49, 0xffff0000, v159
	v_pk_add_f32 v[42:43], v[160:161], v[42:43]
	v_pk_add_f32 v[44:45], v[162:163], v[44:45]
	v_pk_add_f32 v[46:47], v[164:165], v[46:47]
	v_pk_add_f32 v[48:49], v[166:167], v[48:49]
	v_cvt_pk_bf16_f32 v232, v42, v43
	v_cvt_pk_bf16_f32 v233, v44, v45
	v_cvt_pk_bf16_f32 v234, v46, v47
	v_cvt_pk_bf16_f32 v235, v48, v49
	s_nop 1
	v_mfma_f32_16x16x32_bf16 v[0:3], v[232:235], v[188:191], v[0:3]
	v_mfma_f32_16x16x32_bf16 v[4:7], v[232:235], v[192:195], v[4:7]
	v_mfma_f32_16x16x32_bf16 v[8:11], v[232:235], v[196:199], v[8:11]
	v_mfma_f32_16x16x32_bf16 v[12:15], v[232:235], v[228:231], v[12:15]
	global_load_dwordx4 v[144:147], v[236:237], off
	global_load_dwordx4 v[148:151], v[238:239], off offset:1280
	global_load_dwordx4 v[152:155], v[238:239], off offset:1296
	global_load_dwordx4 v[156:159], v[236:237], off offset:64
	global_load_dwordx4 v[160:163], v[238:239], off offset:1408
	global_load_dwordx4 v[164:167], v[238:239], off offset:1424
	global_load_dwordx4 v[168:171], v[20:21], off offset:640
	global_load_dwordx4 v[172:175], v[28:29], off offset:640
	global_load_dwordx4 v[180:183], v[26:27], off offset:640
	global_load_dwordx4 v[184:187], v[24:25], off offset:640
	global_load_dwordx4 v[188:191], v[20:21], off offset:704
	global_load_dwordx4 v[192:195], v[28:29], off offset:704
	global_load_dwordx4 v[196:199], v[26:27], off offset:704
	global_load_dwordx4 v[228:231], v[24:25], off offset:704
	v_lshl_add_u64 v[236:237], v[236:237], 0, s[40:41]
	s_waitcnt vmcnt(14)
	v_lshlrev_b32_e32 v42, 16, v88
	v_and_b32_e32 v43, 0xffff0000, v88
	v_lshlrev_b32_e32 v44, 16, v89
	v_and_b32_e32 v45, 0xffff0000, v89
	v_lshlrev_b32_e32 v46, 16, v90
	v_and_b32_e32 v47, 0xffff0000, v90
	v_lshlrev_b32_e32 v48, 16, v91
	v_and_b32_e32 v49, 0xffff0000, v91
	v_pk_add_f32 v[42:43], v[92:93], v[42:43]
	v_pk_add_f32 v[44:45], v[94:95], v[44:45]
	v_pk_add_f32 v[46:47], v[96:97], v[46:47]
	v_pk_add_f32 v[48:49], v[98:99], v[48:49]
	v_cvt_pk_bf16_f32 v38, v42, v43
	v_cvt_pk_bf16_f32 v39, v44, v45
	v_cvt_pk_bf16_f32 v40, v46, v47
	v_cvt_pk_bf16_f32 v41, v48, v49
	s_nop 1
	v_mfma_f32_16x16x32_bf16 v[0:3], v[38:41], v[112:115], v[0:3]
	v_mfma_f32_16x16x32_bf16 v[4:7], v[38:41], v[116:119], v[4:7]
	v_mfma_f32_16x16x32_bf16 v[8:11], v[38:41], v[120:123], v[8:11]
	v_mfma_f32_16x16x32_bf16 v[12:15], v[38:41], v[124:127], v[12:15]
	v_lshlrev_b32_e32 v42, 16, v100
	v_and_b32_e32 v43, 0xffff0000, v100
	v_lshlrev_b32_e32 v44, 16, v101
	v_and_b32_e32 v45, 0xffff0000, v101
	v_lshlrev_b32_e32 v46, 16, v102
	v_and_b32_e32 v47, 0xffff0000, v102
	v_lshlrev_b32_e32 v48, 16, v103
	v_and_b32_e32 v49, 0xffff0000, v103
	v_pk_add_f32 v[42:43], v[104:105], v[42:43]
	v_pk_add_f32 v[44:45], v[106:107], v[44:45]
	v_pk_add_f32 v[46:47], v[108:109], v[46:47]
	v_pk_add_f32 v[48:49], v[110:111], v[48:49]
	v_cvt_pk_bf16_f32 v232, v42, v43
	v_cvt_pk_bf16_f32 v233, v44, v45
	v_cvt_pk_bf16_f32 v234, v46, v47
	v_cvt_pk_bf16_f32 v235, v48, v49
	s_nop 1
	v_mfma_f32_16x16x32_bf16 v[0:3], v[232:235], v[128:131], v[0:3]
	v_mfma_f32_16x16x32_bf16 v[4:7], v[232:235], v[132:135], v[4:7]
	v_mfma_f32_16x16x32_bf16 v[8:11], v[232:235], v[136:139], v[8:11]
	v_mfma_f32_16x16x32_bf16 v[12:15], v[232:235], v[140:143], v[12:15]
	global_load_dwordx4 v[88:91], v[236:237], off
	global_load_dwordx4 v[92:95], v[238:239], off offset:1536
	global_load_dwordx4 v[96:99], v[238:239], off offset:1552
	global_load_dwordx4 v[100:103], v[236:237], off offset:64
	global_load_dwordx4 v[104:107], v[238:239], off offset:1664
	global_load_dwordx4 v[108:111], v[238:239], off offset:1680
	global_load_dwordx4 v[112:115], v[20:21], off offset:768
	global_load_dwordx4 v[116:119], v[28:29], off offset:768
	global_load_dwordx4 v[120:123], v[26:27], off offset:768
	global_load_dwordx4 v[124:127], v[24:25], off offset:768
	global_load_dwordx4 v[128:131], v[20:21], off offset:832
	global_load_dwordx4 v[132:135], v[28:29], off offset:832
	global_load_dwordx4 v[136:139], v[26:27], off offset:832
	global_load_dwordx4 v[140:143], v[24:25], off offset:832
	v_lshl_add_u64 v[236:237], v[236:237], 0, s[40:41]
	s_waitcnt vmcnt(14)
; DEV float lo_f(unsigned w) { return __uint_as_float(w << 16); }
; DEV float hi_f(unsigned w) { return __uint_as_float(w & 0xFFFF0000u); }
; DEV f32x4 mfma16(bf16x8 a, bf16x8 b, f32x4 c) { return __builtin_amdgcn_mfma_f32_16x16x32_bf16(a, b, c, 0, 0, 0); }
; __device__ void compress_block_item(const Params& P, int l, int bitem, char* smem) {
;     ...
; #pragma unroll 4
;   for (int k2 = 0; k2 < 16; ++k2) {
;     const int ks = w * 16 + k2;
;     const int tl = ks >> 1, d0 = (ks & 1) * 32 + kq * 8;
;     const uint4 raw = *(const uint4*)(src + (size_t)tl * HS + d0);
;     const float4 p0 = *(const float4*)(pos + tl * 64 + d0), p1 = *(const float4*)(pos + tl * 64 + d0 + 4);
;     float v[8];
;     v[0] = lo_f(raw.x) + p0.x; v[1] = hi_f(raw.x) + p0.y; v[2] = lo_f(raw.y) + p0.z; v[3] = hi_f(raw.y) + p0.w;
;     v[4] = lo_f(raw.z) + p1.x; v[5] = hi_f(raw.z) + p1.y; v[6] = lo_f(raw.w) + p1.z; v[7] = hi_f(raw.w) + p1.w;
;     const bf16x8 af = pack8(v);
; #pragma unroll
;     for (int nt = 0; nt < 4; ++nt) {
;       const bf16x8 bfr = *(const bf16x8*)(W1T + (size_t)(nt * 16 + r16) * 2048 + ks * 32 + kq * 8);
;       acc[nt] = mfma16(af, bfr, acc[nt]);
;     }
;   }
	v_lshlrev_b32_e32 v42, 16, v144
	v_and_b32_e32 v43, 0xffff0000, v144
	v_lshlrev_b32_e32 v44, 16, v145
	v_and_b32_e32 v45, 0xffff0000, v145
	v_lshlrev_b32_e32 v46, 16, v146
	v_and_b32_e32 v47, 0xffff0000, v146
	v_lshlrev_b32_e32 v48, 16, v147
	v_and_b32_e32 v49, 0xffff0000, v147
	v_pk_add_f32 v[42:43], v[148:149], v[42:43]
	v_pk_add_f32 v[44:45], v[150:151], v[44:45]
	v_pk_add_f32 v[46:47], v[152:153], v[46:47]
	v_pk_add_f32 v[48:49], v[154:155], v[48:49]
	v_cvt_pk_bf16_f32 v38, v42, v43
	v_cvt_pk_bf16_f32 v39, v44, v45
	v_cvt_pk_bf16_f32 v40, v46, v47
	v_cvt_pk_bf16_f32 v41, v48, v49
	s_nop 1
	v_mfma_f32_16x16x32_bf16 v[0:3], v[38:41], v[168:171], v[0:3]
	v_mfma_f32_16x16x32_bf16 v[4:7], v[38:41], v[172:175], v[4:7]
	v_mfma_f32_16x16x32_bf16 v[8:11], v[38:41], v[180:183], v[8:11]
	v_mfma_f32_16x16x32_bf16 v[12:15], v[38:41], v[184:187], v[12:15]
	v_lshlrev_b32_e32 v42, 16, v156
	v_and_b32_e32 v43, 0xffff0000, v156
	v_lshlrev_b32_e32 v44, 16, v157
	v_and_b32_e32 v45, 0xffff0000, v157
	v_lshlrev_b32_e32 v46, 16, v158
	v_and_b32_e32 v47, 0xffff0000, v158
	v_lshlrev_b32_e32 v48, 16, v159
	v_and_b32_e32 v49, 0xffff0000, v159
	v_pk_add_f32 v[42:43], v[160:161], v[42:43]
	v_pk_add_f32 v[44:45], v[162:163], v[44:45]
	v_pk_add_f32 v[46:47], v[164:165], v[46:47]
	v_pk_add_f32 v[48:49], v[166:167], v[48:49]
	v_cvt_pk_bf16_f32 v232, v42, v43
	v_cvt_pk_bf16_f32 v233, v44, v45
	v_cvt_pk_bf16_f32 v234, v46, v47
	v_cvt_pk_bf16_f32 v235, v48, v49
	s_nop 1
	v_mfma_f32_16x16x32_bf16 v[0:3], v[232:235], v[188:191], v[0:3]
	v_mfma_f32_16x16x32_bf16 v[4:7], v[232:235], v[192:195], v[4:7]
	v_mfma_f32_16x16x32_bf16 v[8:11], v[232:235], v[196:199], v[8:11]
	v_mfma_f32_16x16x32_bf16 v[12:15], v[232:235], v[228:231], v[12:15]
	global_load_dwordx4 v[144:147], v[236:237], off
	global_load_dwordx4 v[148:151], v[238:239], off offset:1792
	global_load_dwordx4 v[152:155], v[238:239], off offset:1808
	global_load_dwordx4 v[156:159], v[236:237], off offset:64
	global_load_dwordx4 v[160:163], v[238:239], off offset:1920
	global_load_dwordx4 v[164:167], v[238:239], off offset:1936
	global_load_dwordx4 v[168:171], v[20:21], off offset:896
	global_load_dwordx4 v[172:175], v[28:29], off offset:896
	global_load_dwordx4 v[180:183], v[26:27], off offset:896
	global_load_dwordx4 v[184:187], v[24:25], off offset:896
	global_load_dwordx4 v[188:191], v[20:21], off offset:960
	global_load_dwordx4 v[192:195], v[28:29], off offset:960
	global_load_dwordx4 v[196:199], v[26:27], off offset:960
	global_load_dwordx4 v[228:231], v[24:25], off offset:960
	v_lshl_add_u64 v[236:237], v[236:237], 0, s[40:41]
	s_waitcnt vmcnt(14)
	v_lshlrev_b32_e32 v42, 16, v88
	v_and_b32_e32 v43, 0xffff0000, v88
	v_lshlrev_b32_e32 v44, 16, v89
	v_and_b32_e32 v45, 0xffff0000, v89
	v_lshlrev_b32_e32 v46, 16, v90
	v_and_b32_e32 v47, 0xffff0000, v90
	v_lshlrev_b32_e32 v48, 16, v91
	v_and_b32_e32 v49, 0xffff0000, v91
	v_pk_add_f32 v[42:43], v[92:93], v[42:43]
	v_pk_add_f32 v[44:45], v[94:95], v[44:45]
	v_pk_add_f32 v[46:47], v[96:97], v[46:47]
	v_pk_add_f32 v[48:49], v[98:99], v[48:49]
	v_cvt_pk_bf16_f32 v38, v42, v43
	v_cvt_pk_bf16_f32 v39, v44, v45
	v_cvt_pk_bf16_f32 v40, v46, v47
	v_cvt_pk_bf16_f32 v41, v48, v49
	s_nop 1
	v_mfma_f32_16x16x32_bf16 v[0:3], v[38:41], v[112:115], v[0:3]
	v_mfma_f32_16x16x32_bf16 v[4:7], v[38:41], v[116:119], v[4:7]
	v_mfma_f32_16x16x32_bf16 v[8:11], v[38:41], v[120:123], v[8:11]
	v_mfma_f32_16x16x32_bf16 v[12:15], v[38:41], v[124:127], v[12:15]
	v_lshlrev_b32_e32 v42, 16, v100
	v_and_b32_e32 v43, 0xffff0000, v100
	v_lshlrev_b32_e32 v44, 16, v101
	v_and_b32_e32 v45, 0xffff0000, v101
	v_lshlrev_b32_e32 v46, 16, v102
	v_and_b32_e32 v47, 0xffff0000, v102
	v_lshlrev_b32_e32 v48, 16, v103
	v_and_b32_e32 v49, 0xffff0000, v103
	v_pk_add_f32 v[42:43], v[104:105], v[42:43]
	v_pk_add_f32 v[44:45], v[106:107], v[44:45]
	v_pk_add_f32 v[46:47], v[108:109], v[46:47]
	v_pk_add_f32 v[48:49], v[110:111], v[48:49]
	v_cvt_pk_bf16_f32 v232, v42, v43
	v_cvt_pk_bf16_f32 v233, v44, v45
	v_cvt_pk_bf16_f32 v234, v46, v47
	v_cvt_pk_bf16_f32 v235, v48, v49
	s_nop 1
	v_mfma_f32_16x16x32_bf16 v[0:3], v[232:235], v[128:131], v[0:3]
	v_mfma_f32_16x16x32_bf16 v[4:7], v[232:235], v[132:135], v[4:7]
	v_mfma_f32_16x16x32_bf16 v[8:11], v[232:235], v[136:139], v[8:11]
	v_mfma_f32_16x16x32_bf16 v[12:15], v[232:235], v[140:143], v[12:15]
	s_waitcnt vmcnt(0)
; DEV float lo_f(unsigned w) { return __uint_as_float(w << 16); }
; DEV float hi_f(unsigned w) { return __uint_as_float(w & 0xFFFF0000u); }
; DEV f32x4 mfma16(bf16x8 a, bf16x8 b, f32x4 c) { return __builtin_amdgcn_mfma_f32_16x16x32_bf16(a, b, c, 0, 0, 0); }
; __device__ void compress_block_item(const Params& P, int l, int bitem, char* smem) {
;     ...
; #pragma unroll 4
;   for (int k2 = 0; k2 < 16; ++k2) {
;     const int ks = w * 16 + k2;
;     const int tl = ks >> 1, d0 = (ks & 1) * 32 + kq * 8;
;     const uint4 raw = *(const uint4*)(src + (size_t)tl * HS + d0);
;     const float4 p0 = *(const float4*)(pos + tl * 64 + d0), p1 = *(const float4*)(pos + tl * 64 + d0 + 4);
;     float v[8];
;     v[0] = lo_f(raw.x) + p0.x; v[1] = hi_f(raw.x) + p0.y; v[2] = lo_f(raw.y) + p0.z; v[3] = hi_f(raw.y) + p0.w;
;     v[4] = lo_f(raw.z) + p1.x; v[5] = hi_f(raw.z) + p1.y; v[6] = lo_f(raw.w) + p1.z; v[7] = hi_f(raw.w) + p1.w;
;     const bf16x8 af = pack8(v);
; #pragma unroll
;     for (int nt = 0; nt < 4; ++nt) {
;       const bf16x8 bfr = *(const bf16x8*)(W1T + (size_t)(nt * 16 + r16) * 2048 + ks * 32 + kq * 8);
;       acc[nt] = mfma16(af, bfr, acc[nt]);
;     }
;   }
;   const float* b1 = (kv ? P.cmpv_b1 : P.cmpk_b1) + l * 64;
;   const float* w2 = (kv ? P.cmpv_w2 : P.cmpk_w2) + l * 64 * 64;
;   const float* b2 = (kv ? P.cmpv_b2 : P.cmpk_b2) + l * 64;
	v_lshlrev_b32_e32 v42, 16, v144
	v_and_b32_e32 v43, 0xffff0000, v144
	v_lshlrev_b32_e32 v44, 16, v145
	v_and_b32_e32 v45, 0xffff0000, v145
	v_lshlrev_b32_e32 v46, 16, v146
	v_and_b32_e32 v47, 0xffff0000, v146
	v_lshlrev_b32_e32 v48, 16, v147
	v_and_b32_e32 v49, 0xffff0000, v147
	v_pk_add_f32 v[42:43], v[148:149], v[42:43]
	v_pk_add_f32 v[44:45], v[150:151], v[44:45]
	v_pk_add_f32 v[46:47], v[152:153], v[46:47]
	v_pk_add_f32 v[48:49], v[154:155], v[48:49]
	v_cvt_pk_bf16_f32 v38, v42, v43
	v_cvt_pk_bf16_f32 v39, v44, v45
	v_cvt_pk_bf16_f32 v40, v46, v47
	v_cvt_pk_bf16_f32 v41, v48, v49
	s_nop 1
	v_mfma_f32_16x16x32_bf16 v[0:3], v[38:41], v[168:171], v[0:3]
	v_mfma_f32_16x16x32_bf16 v[4:7], v[38:41], v[172:175], v[4:7]
	v_mfma_f32_16x16x32_bf16 v[8:11], v[38:41], v[180:183], v[8:11]
	v_mfma_f32_16x16x32_bf16 v[12:15], v[38:41], v[184:187], v[12:15]
	v_lshlrev_b32_e32 v42, 16, v156
	v_and_b32_e32 v43, 0xffff0000, v156
	v_lshlrev_b32_e32 v44, 16, v157
	v_and_b32_e32 v45, 0xffff0000, v157
	v_lshlrev_b32_e32 v46, 16, v158
	v_and_b32_e32 v47, 0xffff0000, v158
	v_lshlrev_b32_e32 v48, 16, v159
	v_and_b32_e32 v49, 0xffff0000, v159
	v_pk_add_f32 v[42:43], v[160:161], v[42:43]
	v_pk_add_f32 v[44:45], v[162:163], v[44:45]
	v_pk_add_f32 v[46:47], v[164:165], v[46:47]
	v_pk_add_f32 v[48:49], v[166:167], v[48:49]
	v_cvt_pk_bf16_f32 v232, v42, v43
	v_cvt_pk_bf16_f32 v233, v44, v45
	v_cvt_pk_bf16_f32 v234, v46, v47
	v_cvt_pk_bf16_f32 v235, v48, v49
	s_nop 1
	v_mfma_f32_16x16x32_bf16 v[0:3], v[232:235], v[188:191], v[0:3]
	v_mfma_f32_16x16x32_bf16 v[4:7], v[232:235], v[192:195], v[4:7]
	v_mfma_f32_16x16x32_bf16 v[8:11], v[232:235], v[196:199], v[8:11]
	v_mfma_f32_16x16x32_bf16 v[12:15], v[232:235], v[228:231], v[12:15]
	s_and_b32 s96, s6, 0x7f0
	s_lshl_b32 s2, s56, 8
	v_readlane_b32 s40, v251, 26
	v_readlane_b32 s68, v252, 36
	s_and_b64 s[38:39], s[38:39], exec
	v_readlane_b32 s41, v251, 27
	v_readlane_b32 s42, v251, 28
	v_readlane_b32 s43, v251, 29
	v_readlane_b32 s44, v251, 30
	v_readlane_b32 s45, v251, 31
	v_readlane_b32 s46, v251, 32
	v_readlane_b32 s47, v251, 33
	v_readlane_b32 s48, v251, 34
	v_readlane_b32 s49, v251, 35
	v_readlane_b32 s50, v251, 36
	v_readlane_b32 s51, v251, 37
	v_readlane_b32 s52, v251, 38
	v_readlane_b32 s53, v251, 39
	v_readlane_b32 s54, v251, 40
	v_readlane_b32 s55, v251, 41
	v_readlane_b32 s69, v252, 37
	v_readlane_b32 s70, v252, 38
	v_readlane_b32 s71, v252, 39
	v_readlane_b32 s72, v252, 40
	v_readlane_b32 s73, v252, 41
	v_readlane_b32 s74, v252, 42
	v_readlane_b32 s75, v252, 43
	v_readlane_b32 s76, v252, 44
	v_readlane_b32 s77, v252, 45
	v_readlane_b32 s78, v252, 46
	v_readlane_b32 s79, v252, 47
	v_readlane_b32 s80, v252, 48
	v_readlane_b32 s81, v252, 49
	v_readlane_b32 s82, v252, 50
	v_readlane_b32 s83, v252, 51
	s_cselect_b32 s38, s49, s71
	v_readlane_b32 s40, v251, 26
	v_readlane_b32 s68, v252, 36
	v_readlane_b32 s41, v251, 27
	v_readlane_b32 s42, v251, 28
	v_readlane_b32 s43, v251, 29
	v_readlane_b32 s44, v251, 30
	v_readlane_b32 s45, v251, 31
	v_readlane_b32 s46, v251, 32
	v_readlane_b32 s47, v251, 33
	v_readlane_b32 s48, v251, 34
	v_readlane_b32 s49, v251, 35
	v_readlane_b32 s50, v251, 36
	v_readlane_b32 s51, v251, 37
	v_readlane_b32 s52, v251, 38
	v_readlane_b32 s53, v251, 39
	v_readlane_b32 s54, v251, 40
	v_readlane_b32 s55, v251, 41
	v_readlane_b32 s69, v252, 37
	v_readlane_b32 s70, v252, 38
	v_readlane_b32 s71, v252, 39
	v_readlane_b32 s72, v252, 40
	v_readlane_b32 s73, v252, 41
	v_readlane_b32 s74, v252, 42
	v_readlane_b32 s75, v252, 43
	v_readlane_b32 s76, v252, 44
	v_readlane_b32 s77, v252, 45
	v_readlane_b32 s78, v252, 46
	v_readlane_b32 s79, v252, 47
	v_readlane_b32 s80, v252, 48
	v_readlane_b32 s81, v252, 49
	v_readlane_b32 s82, v252, 50
	v_readlane_b32 s83, v252, 51
	s_cselect_b32 s39, s48, s70
	v_readlane_b32 s40, v251, 26
	v_readlane_b32 s68, v252, 36
	v_readlane_b32 s41, v251, 27
	v_readlane_b32 s44, v251, 30
	v_readlane_b32 s45, v251, 31
	v_readlane_b32 s46, v251, 32
	v_readlane_b32 s47, v251, 33
	v_readlane_b32 s48, v251, 34
	v_readlane_b32 s49, v251, 35
	v_readlane_b32 s50, v251, 36
	v_readlane_b32 s51, v251, 37
	v_readlane_b32 s52, v251, 38
	v_readlane_b32 s53, v251, 39
	v_readlane_b32 s54, v251, 40
	v_readlane_b32 s55, v251, 41
	v_readlane_b32 s69, v252, 37
	v_readlane_b32 s70, v252, 38
	v_readlane_b32 s71, v252, 39
	v_readlane_b32 s72, v252, 40
	v_readlane_b32 s73, v252, 41
	v_readlane_b32 s74, v252, 42
	v_readlane_b32 s75, v252, 43
	v_readlane_b32 s76, v252, 44
	v_readlane_b32 s77, v252, 45
	v_readlane_b32 s78, v252, 46
	v_readlane_b32 s79, v252, 47
	v_readlane_b32 s80, v252, 48
	v_readlane_b32 s81, v252, 49
	v_readlane_b32 s82, v252, 50
	v_readlane_b32 s83, v252, 51
	s_cselect_b32 s41, s51, s73
	v_readlane_b32 s44, v251, 26
	v_readlane_b32 s68, v252, 36
	v_readlane_b32 s42, v251, 28
	v_readlane_b32 s45, v251, 27
	v_readlane_b32 s46, v251, 28
	v_readlane_b32 s47, v251, 29
	v_readlane_b32 s48, v251, 30
	v_readlane_b32 s49, v251, 31
	v_readlane_b32 s50, v251, 32
	v_readlane_b32 s51, v251, 33
	v_readlane_b32 s52, v251, 34
	v_readlane_b32 s53, v251, 35
	v_readlane_b32 s54, v251, 36
	v_readlane_b32 s55, v251, 37
	v_readlane_b32 s56, v251, 38
	v_readlane_b32 s57, v251, 39
	v_readlane_b32 s58, v251, 40
	v_readlane_b32 s59, v251, 41
	v_readlane_b32 s69, v252, 37
	v_readlane_b32 s70, v252, 38
	v_readlane_b32 s71, v252, 39
	v_readlane_b32 s72, v252, 40
	v_readlane_b32 s73, v252, 41
	v_readlane_b32 s74, v252, 42
	v_readlane_b32 s75, v252, 43
	v_readlane_b32 s76, v252, 44
	v_readlane_b32 s77, v252, 45
	v_readlane_b32 s78, v252, 46
	v_readlane_b32 s79, v252, 47
	v_readlane_b32 s80, v252, 48
	v_readlane_b32 s81, v252, 49
; __device__ void compress_block_item(const Params& P, int l, int bitem, char* smem) {
;     ...
;   const float* b1 = (kv ? P.cmpv_b1 : P.cmpk_b1) + l * 64;
;   const float* w2 = (kv ? P.cmpv_w2 : P.cmpk_w2) + l * 64 * 64;
;   const float* b2 = (kv ? P.cmpv_b2 : P.cmpk_b2) + l * 64;
;   __syncthreads();
; #pragma unroll
;   for (int nt = 0; nt < 4; ++nt)
; #pragma unroll
;     for (int r = 0; r < 4; ++r) part[w * 1024 + (kq * 4 + r) * 64 + nt * 16 + r16] = acc[nt][r];
;   __syncthreads();
; #pragma unroll
;   for (int k = 0; k < 4; ++k) {
;     const int idx = tid + 256 * k;
;     const float sum = part[idx] + part[1024 + idx] + part[2048 + idx] + part[3072 + idx];
;     hid[idx] = gelu_t(sum + b1[idx & 63]);
;   }
	v_readlane_b32 s82, v252, 50
	v_readlane_b32 s83, v252, 51
	s_cselect_b32 s42, s54, s72
	v_readlane_b32 s44, v251, 26
	v_readlane_b32 s68, v252, 36
	v_readlane_b32 s45, v251, 27
	v_readlane_b32 s46, v251, 28
	v_readlane_b32 s47, v251, 29
	v_readlane_b32 s48, v251, 30
	v_readlane_b32 s49, v251, 31
	v_readlane_b32 s50, v251, 32
	v_readlane_b32 s51, v251, 33
	v_readlane_b32 s52, v251, 34
	v_readlane_b32 s53, v251, 35
	v_readlane_b32 s54, v251, 36
	v_readlane_b32 s55, v251, 37
	v_readlane_b32 s56, v251, 38
	v_readlane_b32 s57, v251, 39
	v_readlane_b32 s58, v251, 40
	v_readlane_b32 s59, v251, 41
	v_readlane_b32 s75, v252, 43
	v_readlane_b32 s69, v252, 37
	v_readlane_b32 s70, v252, 38
	v_readlane_b32 s71, v252, 39
	v_readlane_b32 s72, v252, 40
	v_readlane_b32 s73, v252, 41
	v_readlane_b32 s74, v252, 42
	v_readlane_b32 s76, v252, 44
	v_readlane_b32 s77, v252, 45
	v_readlane_b32 s78, v252, 46
	v_readlane_b32 s79, v252, 47
	v_readlane_b32 s80, v252, 48
	v_readlane_b32 s81, v252, 49
	v_readlane_b32 s82, v252, 50
	v_readlane_b32 s83, v252, 51
	s_cselect_b32 s40, s57, s75
	v_readlane_b32 s44, v251, 26
	v_readlane_b32 s46, v251, 28
	v_readlane_b32 s47, v251, 29
	v_readlane_b32 s68, v252, 36
	v_readlane_b32 s43, v251, 29
	v_readlane_b32 s56, v251, 38
	v_readlane_b32 s74, v252, 42
	v_lshlrev_b32_e32 v16, 12, v33
	v_lshlrev_b32_e32 v17, 10, v36
	v_lshlrev_b32_e32 v18, 2, v35
	v_readlane_b32 s46, v248, 23
	v_readlane_b32 s45, v251, 27
	s_cselect_b32 s43, s56, s74
	v_or3_b32 v16, v16, v17, v18
	v_readlane_b32 s47, v248, 24
	s_add_u32 s44, s39, s46
	s_barrier
	ds_write2_b32 v16, v0, v4 offset1:16
	ds_write2_b32 v16, v1, v5 offset0:64 offset1:80
	ds_write2_b32 v16, v2, v6 offset0:128 offset1:144
	ds_write2_b32 v16, v3, v7 offset0:192 offset1:208
	ds_write2_b32 v16, v8, v12 offset0:32 offset1:48
	ds_write2_b32 v16, v9, v13 offset0:96 offset1:112
	ds_write2_b32 v16, v10, v14 offset0:160 offset1:176
	ds_write2_b32 v16, v11, v15 offset0:224 offset1:240
	s_addc_u32 s45, s38, s47
	v_lshlrev_b32_e32 v176, 2, v32
	v_lshlrev_b32_e32 v0, 2, v34
	s_waitcnt lgkmcnt(0)
	s_barrier
	ds_read2st64_b32 v[2:3], v0 offset1:4
	ds_read2st64_b32 v[4:5], v0 offset0:16 offset1:20
	global_load_dword v10, v176, s[44:45]
	ds_read2st64_b32 v[6:7], v0 offset0:32 offset1:36
	ds_read2st64_b32 v[8:9], v0 offset0:48 offset1:52
	v_readlane_b32 s38, v248, 25
	s_waitcnt lgkmcnt(2)
	v_add_f32_e32 v1, v2, v4
	v_readlane_b32 s39, v248, 26
	s_waitcnt lgkmcnt(1)
	v_add_f32_e32 v1, v1, v6
	s_waitcnt lgkmcnt(0)
	v_add_f32_e32 v1, v1, v8
	s_add_u32 s38, s42, s38
	s_addc_u32 s39, s41, s39
	v_readlane_b32 s69, v252, 37
	v_readlane_b32 s70, v252, 38
	v_readlane_b32 s71, v252, 39
	v_readlane_b32 s72, v252, 40
	v_readlane_b32 s73, v252, 41
	v_readlane_b32 s75, v252, 43
	v_readlane_b32 s76, v252, 44
	v_readlane_b32 s77, v252, 45
	v_readlane_b32 s78, v252, 46
	v_readlane_b32 s79, v252, 47
	v_readlane_b32 s80, v252, 48
	v_readlane_b32 s81, v252, 49
	v_readlane_b32 s82, v252, 50
	v_readlane_b32 s83, v252, 51
	v_readlane_b32 s68, v249, 21
	v_readlane_b32 s78, v249, 31
	v_readlane_b32 s79, v249, 32
	v_readlane_b32 s69, v249, 22
	v_readlane_b32 s70, v249, 23
	v_readlane_b32 s71, v249, 24
	v_readlane_b32 s72, v249, 25
	v_readlane_b32 s73, v249, 26
	v_readlane_b32 s74, v249, 27
	v_readlane_b32 s75, v249, 28
	v_readlane_b32 s76, v249, 29
	v_readlane_b32 s77, v249, 30
	v_readlane_b32 s80, v249, 33
	v_readlane_b32 s81, v249, 34
	v_readlane_b32 s82, v249, 35
	v_readlane_b32 s83, v249, 36
	v_readlane_b32 s48, v251, 30
	v_readlane_b32 s49, v251, 31
	v_readlane_b32 s50, v251, 32
	v_readlane_b32 s51, v251, 33
	v_readlane_b32 s52, v251, 34
	v_readlane_b32 s53, v251, 35
	v_readlane_b32 s54, v251, 36
	v_readlane_b32 s55, v251, 37
	v_readlane_b32 s57, v251, 39
	v_readlane_b32 s58, v251, 40
	v_readlane_b32 s59, v251, 41
	s_waitcnt vmcnt(0)
	v_add_f32_e32 v1, v1, v10
	v_mul_f32_e32 v2, 0x3d372713, v1
	v_mul_f32_e32 v2, v1, v2
	v_fma_f32 v2, v1, v2, v1
	v_mul_f32_e32 v2, 0x3f4c422a, v2
	v_add_f32_e32 v2, v2, v2
	v_mul_f32_e32 v2, 0x3fb8aa3b, v2
	v_exp_f32_e32 v2, v2
	v_mul_f32_e32 v1, 0.5, v1
	v_add_f32_e32 v2, 1.0, v2
	v_div_scale_f32 v4, s[44:45], v2, v2, 2.0
	v_rcp_f32_e32 v6, v4
	s_nop 0
	v_fma_f32 v8, -v4, v6, 1.0
	v_fmac_f32_e32 v6, v8, v6
	v_div_scale_f32 v8, vcc, 2.0, v2, 2.0
	v_mul_f32_e32 v11, v8, v6
	v_fma_f32 v12, -v4, v11, v8
	v_fmac_f32_e32 v11, v12, v6
	v_fma_f32 v4, -v4, v11, v8
	v_div_fmas_f32 v4, v4, v6, v11
	v_div_fixup_f32 v2, v4, v2, 2.0
	v_sub_f32_e32 v2, 1.0, v2
	v_add_f32_e32 v2, 1.0, v2
	v_mul_f32_e32 v1, v1, v2
	v_add_f32_e32 v2, v3, v5
	v_add_f32_e32 v2, v2, v7
	v_add_f32_e32 v2, v2, v9
	v_add_f32_e32 v2, v10, v2
	v_mul_f32_e32 v3, 0x3d372713, v2
	v_mul_f32_e32 v3, v2, v3
	v_fma_f32 v3, v2, v3, v2
	v_mul_f32_e32 v3, 0x3f4c422a, v3
	v_add_f32_e32 v3, v3, v3
	v_mul_f32_e32 v3, 0x3fb8aa3b, v3
	v_exp_f32_e32 v3, v3
	v_mul_f32_e32 v2, 0.5, v2
	v_add_f32_e32 v3, 1.0, v3
	v_div_scale_f32 v4, s[44:45], v3, v3, 2.0
	v_rcp_f32_e32 v5, v4
	s_nop 0
	v_fma_f32 v6, -v4, v5, 1.0
	v_fmac_f32_e32 v5, v6, v5
	v_div_scale_f32 v6, vcc, 2.0, v3, 2.0
	v_mul_f32_e32 v7, v6, v5
	v_fma_f32 v8, -v4, v7, v6
	v_fmac_f32_e32 v7, v8, v5
	v_fma_f32 v4, -v4, v7, v6
	v_div_fmas_f32 v4, v4, v5, v7
	v_div_fixup_f32 v3, v4, v3, 2.0
	v_sub_f32_e32 v3, 1.0, v3
	v_add_f32_e32 v3, 1.0, v3
	v_mul_f32_e32 v2, v2, v3
	ds_write2st64_b32 v0, v1, v2 offset0:64 offset1:68
	ds_read2st64_b32 v[2:3], v0 offset0:8 offset1:12
	ds_read2st64_b32 v[4:5], v0 offset0:24 offset1:28
	ds_read2st64_b32 v[6:7], v0 offset0:40 offset1:44
	ds_read2st64_b32 v[8:9], v0 offset0:56 offset1:60
	s_waitcnt lgkmcnt(2)
; __device__ void compress_block_item(const Params& P, int l, int bitem, char* smem) {
;     ...
; #pragma unroll
;   for (int k = 0; k < 4; ++k) {
;     const int idx = tid + 256 * k;
;     const float sum = part[idx] + part[1024 + idx] + part[2048 + idx] + part[3072 + idx];
;     hid[idx] = gelu_t(sum + b1[idx & 63]);
;   }
;   __syncthreads();
;   float w2c[64];
; #pragma unroll
;   for (int k = 0; k < 64; ++k) w2c[k] = w2[k * 64 + lane];
;   const float bo = b2[lane];
	v_add_f32_e32 v1, v2, v4
	s_waitcnt lgkmcnt(1)
	v_add_f32_e32 v1, v1, v6
	s_waitcnt lgkmcnt(0)
	v_add_f32_e32 v1, v1, v8
	v_add_f32_e32 v1, v10, v1
	v_mul_f32_e32 v2, 0x3d372713, v1
	v_mul_f32_e32 v2, v1, v2
	v_fma_f32 v2, v1, v2, v1
	v_mul_f32_e32 v2, 0x3f4c422a, v2
	v_add_f32_e32 v2, v2, v2
	v_mul_f32_e32 v2, 0x3fb8aa3b, v2
	v_exp_f32_e32 v2, v2
	v_mul_f32_e32 v1, 0.5, v1
	v_add_f32_e32 v2, 1.0, v2
	v_div_scale_f32 v4, s[44:45], v2, v2, 2.0
	v_rcp_f32_e32 v6, v4
	s_nop 0
	v_fma_f32 v8, -v4, v6, 1.0
	v_fmac_f32_e32 v6, v8, v6
	v_div_scale_f32 v8, vcc, 2.0, v2, 2.0
	v_mul_f32_e32 v11, v8, v6
	v_fma_f32 v12, -v4, v11, v8
	v_fmac_f32_e32 v11, v12, v6
	v_fma_f32 v4, -v4, v11, v8
	v_div_fmas_f32 v4, v4, v6, v11
	v_div_fixup_f32 v2, v4, v2, 2.0
	v_sub_f32_e32 v2, 1.0, v2
	v_add_f32_e32 v2, 1.0, v2
	v_mul_f32_e32 v1, v1, v2
	v_add_f32_e32 v2, v3, v5
	v_add_f32_e32 v2, v2, v7
	v_add_f32_e32 v2, v2, v9
	v_add_f32_e32 v2, v10, v2
	v_mul_f32_e32 v3, 0x3d372713, v2
	v_mul_f32_e32 v3, v2, v3
	v_fma_f32 v3, v2, v3, v2
	v_mul_f32_e32 v3, 0x3f4c422a, v3
	v_add_f32_e32 v3, v3, v3
	v_mul_f32_e32 v3, 0x3fb8aa3b, v3
	v_exp_f32_e32 v3, v3
	v_mul_f32_e32 v2, 0.5, v2
	v_add_f32_e32 v3, 1.0, v3
	v_div_scale_f32 v4, s[44:45], v3, v3, 2.0
	v_rcp_f32_e32 v5, v4
	s_mov_b32 s44, 0
	v_fma_f32 v6, -v4, v5, 1.0
	v_fmac_f32_e32 v5, v6, v5
	v_div_scale_f32 v6, vcc, 2.0, v3, 2.0
	v_mul_f32_e32 v7, v6, v5
	v_fma_f32 v8, -v4, v7, v6
	v_fmac_f32_e32 v7, v8, v5
	v_fma_f32 v4, -v4, v7, v6
	v_div_fmas_f32 v4, v4, v5, v7
	v_div_fixup_f32 v3, v4, v3, 2.0
	v_sub_f32_e32 v3, 1.0, v3
	v_add_f32_e32 v3, 1.0, v3
	v_mul_f32_e32 v2, v2, v3
	ds_write2st64_b32 v0, v1, v2 offset0:72 offset1:76
	s_waitcnt lgkmcnt(0)
	s_barrier
	v_lshl_add_u64 v[0:1], s[38:39], 0, v[176:177]
	global_load_dword v3, v176, s[38:39]
	global_load_dword v4, v176, s[38:39] offset:256
	global_load_dword v5, v176, s[38:39] offset:512
	global_load_dword v6, v176, s[38:39] offset:768
	global_load_dword v7, v176, s[38:39] offset:1024
	global_load_dword v8, v176, s[38:39] offset:1280
	global_load_dword v9, v176, s[38:39] offset:1536
	global_load_dword v10, v176, s[38:39] offset:1792
	global_load_dword v11, v176, s[38:39] offset:2048
	global_load_dword v12, v176, s[38:39] offset:2304
	global_load_dword v13, v176, s[38:39] offset:2560
	global_load_dword v14, v176, s[38:39] offset:2816
	global_load_dword v15, v176, s[38:39] offset:3072
	global_load_dword v16, v176, s[38:39] offset:3328
	global_load_dword v17, v176, s[38:39] offset:3584
	global_load_dword v18, v176, s[38:39] offset:3840
	s_movk_i32 s38, 0x1000
	v_add_co_u32_e32 v36, vcc, s38, v0
	s_movk_i32 s38, 0x3000
	s_nop 0
	v_addc_co_u32_e32 v37, vcc, 0, v1, vcc
	v_add_co_u32_e32 v52, vcc, s65, v0
	v_lshl_add_u32 v2, v33, 2, s96
	s_nop 0
	v_addc_co_u32_e32 v53, vcc, 0, v1, vcc
	global_load_dword v19, v[52:53], off offset:-4096
	global_load_dword v20, v[36:37], off offset:256
	global_load_dword v21, v[36:37], off offset:512
	global_load_dword v22, v[36:37], off offset:768
	global_load_dword v23, v[36:37], off offset:1024
	global_load_dword v24, v[36:37], off offset:1280
	global_load_dword v25, v[36:37], off offset:1536
	global_load_dword v26, v[36:37], off offset:1792
	global_load_dword v27, v[36:37], off offset:2048
	global_load_dword v28, v[36:37], off offset:2304
	global_load_dword v29, v[36:37], off offset:2560
	global_load_dword v30, v[36:37], off offset:2816
	global_load_dword v31, v[36:37], off offset:3072
	global_load_dword v34, v[36:37], off offset:3328
	global_load_dword v35, v[36:37], off offset:3584
	s_nop 0
	global_load_dword v36, v[36:37], off offset:3840
	s_nop 0
	global_load_dword v37, v[52:53], off
	global_load_dword v38, v[52:53], off offset:256
	global_load_dword v39, v[52:53], off offset:512
	global_load_dword v40, v[52:53], off offset:768
	global_load_dword v41, v[52:53], off offset:1024
	global_load_dword v42, v[52:53], off offset:1280
	global_load_dword v43, v[52:53], off offset:1536
	global_load_dword v44, v[52:53], off offset:1792
	global_load_dword v45, v[52:53], off offset:2048
	global_load_dword v46, v[52:53], off offset:2304
	global_load_dword v47, v[52:53], off offset:2560
	global_load_dword v48, v[52:53], off offset:2816
	global_load_dword v49, v[52:53], off offset:3072
	global_load_dword v50, v[52:53], off offset:3328
	global_load_dword v51, v[52:53], off offset:3584
	s_nop 0
	global_load_dword v52, v[52:53], off offset:3840
	v_add_co_u32_e32 v0, vcc, s38, v0
	s_add_u32 s38, s43, s46
	s_nop 0
	v_addc_co_u32_e32 v1, vcc, 0, v1, vcc
	global_load_dword v53, v[0:1], off
	global_load_dword v54, v[0:1], off offset:256
	global_load_dword v55, v[0:1], off offset:512
	global_load_dword v56, v[0:1], off offset:768
	global_load_dword v57, v[0:1], off offset:1024
	global_load_dword v58, v[0:1], off offset:1280
	global_load_dword v59, v[0:1], off offset:1536
	global_load_dword v60, v[0:1], off offset:1792
	global_load_dword v61, v[0:1], off offset:2048
	global_load_dword v62, v[0:1], off offset:2304
	global_load_dword v63, v[0:1], off offset:2560
	global_load_dword v64, v[0:1], off offset:2816
	global_load_dword v65, v[0:1], off offset:3072
	global_load_dword v66, v[0:1], off offset:3328
	global_load_dword v67, v[0:1], off offset:3584
	global_load_dword v68, v[0:1], off offset:3840
	s_addc_u32 s39, s40, s47
	global_load_dword v69, v176, s[38:39]
	v_lshlrev_b32_e32 v176, 1, v32
	v_lshl_add_u64 v[0:1], s[78:79], 0, v[176:177]
	v_or_b32_e32 v32, s64, v32
	v_lshl_add_u32 v33, v33, 10, v225
	s_waitcnt vmcnt(0)
	s_branch .LBB0_304
